# work queue: redundant second rendezvous after the s_item read removed (item-internal barriers already order the next write)
# speedup vs baseline: 1.0075x; 1.0075x over previous
.LBB0_112:
	s_or_b64 exec, exec, s[14:15]
	s_waitcnt lgkmcnt(0)
	s_barrier
	s_waitcnt vmcnt(7)
	ds_read_b32 v0, v174
	s_movk_i32 s5, 0x22ff
	s_mov_b64 s[14:15], -1
	s_waitcnt lgkmcnt(0)
	v_cmp_lt_i32_e32 vcc, s5, v0
	v_readfirstlane_b32 s54, v0
	s_cbranch_vccnz .LBB0_107
	v_mov_b32_e32 v97, v192
	s_cmpk_gt_i32 s54, 0x9ff
	v_and_b32_e32 v98, 63, v97
	v_ashrrev_i32_e32 v194, 6, v97
	v_and_b32_e32 v195, 31, v97
	v_bfe_u32 v193, v97, 5, 1
	s_cbranch_scc0 .LBB0_193
	s_cmpk_gt_u32 s54, 0x18ff
	s_cbranch_scc0 .LBB0_188
	s_add_i32 s5, s54, 0xffffe700
	s_lshr_b32 s14, s5, 2
	s_add_i32 s15, s14, 0xfffffe00
	s_lshr_b32 s15, s15, 5
	s_and_b32 s56, s54, 3
	s_add_i32 s15, s15, 8
	s_lshr_b32 s16, s5, 8
	s_cmpk_lt_u32 s5, 0x800
	s_cselect_b32 s5, 63, 31
	s_cselect_b32 s15, s16, s15
	s_cselect_b32 s26, 6, 5
	s_and_b32 s55, s14, s5
	s_lshl_b32 s5, s15, 12
	s_add_i32 s5, s5, 0x8000
	s_lshl_b32 s16, s15, 13
	s_cmp_gt_u32 s15, 7
	s_cselect_b64 s[42:43], -1, 0
	s_and_b64 s[14:15], s[42:43], exec
	s_waitcnt vmcnt(3)
	v_ashrrev_i32_e32 v8, 2, v97
	s_cselect_b32 s5, s5, s16
	v_lshlrev_b32_e32 v0, s26, v8
	s_or_b32 s27, s5, s55
	v_add_u32_e32 v0, s27, v0
	v_ashrrev_i32_e32 v1, 31, v0
	v_readlane_b32 s14, v255, 2
	v_lshlrev_b64 v[0:1], 9, v[0:1]
	v_readlane_b32 s15, v255, 3
	v_lshlrev_b32_e32 v2, 4, v97
	s_lshl_b32 s30, s56, 7
	v_lshl_add_u64 v[0:1], s[14:15], 0, v[0:1]
	v_and_b32_e32 v10, 48, v2
	v_lshl_add_u64 v[0:1], v[0:1], 0, s[30:31]
	v_lshlrev_b32_e32 v168, 1, v10
	v_lshl_add_u64 v[4:5], v[0:1], 0, v[168:169]
	global_load_dwordx4 v[0:3], v[4:5], off offset:16
	s_nop 0
	global_load_dwordx4 v[4:7], v[4:5], off
	v_mul_lo_u32 v8, v8, s60
	v_cmp_lt_u32_e32 vcc, 32, v10
	v_add_u32_e32 v9, v8, v168
	s_and_saveexec_b64 s[14:15], vcc
	s_xor_b64 s[14:15], exec, s[14:15]
	s_cbranch_execz .LBB0_117
	s_waitcnt vmcnt(0)
	v_xor_b32_e32 v11, 0xffff8000, v4
	v_sub_u32_e32 v12, v8, v168
	ds_write_b16 v9, v4 offset:64
	ds_write_b16 v12, v11 offset:320
